# GEMM2: no wave-realigning barriers after a workgroup's last tile (only stores follow)
# speedup vs baseline: 1.0051x; 1.0019x over previous
.LBB0_528:
	s_add_i32 s61, 16, 0x10000
	v_add_u32_e32 v172, s61, v159
	ds_read_b128 v[160:163], v172
	ds_read_b128 v[164:167], v172 offset:1024
	ds_read_b128 v[168:171], v172 offset:2048
	ds_read_b128 v[172:175], v172 offset:3072
	v_lshl_add_u64 v[226:227], v[146:147], 0, s[54:55]
	s_add_i32 s60, s57, 0xc000
	v_lshl_add_u64 v[210:211], v[226:227], 0, s[42:43]
	s_mov_b32 m0, s60
	v_lshl_add_u64 v[228:229], v[148:149], 0, s[54:55]
	s_add_i32 s58, s57, 0xe000
	ds_read_b128 v[176:179], v158
	ds_read_b128 v[180:183], v158 offset:1024
	ds_read_b128 v[184:187], v158 offset:2048
	ds_read_b128 v[188:191], v158 offset:3072
	ds_read_b128 v[192:195], v158 offset:4096
	ds_read_b128 v[198:201], v158 offset:5120
	ds_read_b128 v[202:205], v158 offset:6144
	ds_read_b128 v[206:209], v158 offset:7168
	global_load_lds_dwordx4 v[210:211], off
	v_lshl_add_u64 v[210:211], v[228:229], 0, s[42:43]
	s_mov_b32 m0, s58
	s_nop 0
	global_load_lds_dwordx4 v[210:211], off
	s_waitcnt lgkmcnt(8)
	s_barrier
	s_waitcnt lgkmcnt(0)
	s_setprio 1
	s_waitcnt lgkmcnt(0)
	v_mfma_f32_16x16x32_bf16 v[14:17], v[160:163], v[176:179], v[14:17]
	v_mfma_f32_16x16x32_bf16 v[10:13], v[168:171], v[176:179], v[10:13]
	v_mfma_f32_16x16x32_bf16 v[30:33], v[160:163], v[184:187], v[30:33]
	v_mfma_f32_16x16x32_bf16 v[26:29], v[168:171], v[184:187], v[26:29]
	v_mfma_f32_16x16x32_bf16 v[62:65], v[160:163], v[192:195], v[62:65]
	v_mfma_f32_16x16x32_bf16 v[54:57], v[168:171], v[192:195], v[54:57]
	v_mfma_f32_16x16x32_bf16 v[94:97], v[160:163], v[202:205], v[94:97]
	v_mfma_f32_16x16x32_bf16 v[86:89], v[168:171], v[202:205], v[86:89]
	v_mfma_f32_16x16x32_bf16 v[14:17], v[164:167], v[180:183], v[14:17]
	v_mfma_f32_16x16x32_bf16 v[10:13], v[172:175], v[180:183], v[10:13]
	v_mfma_f32_16x16x32_bf16 v[30:33], v[164:167], v[188:191], v[30:33]
	v_mfma_f32_16x16x32_bf16 v[26:29], v[172:175], v[188:191], v[26:29]
	v_mfma_f32_16x16x32_bf16 v[62:65], v[164:167], v[198:201], v[62:65]
	v_mfma_f32_16x16x32_bf16 v[54:57], v[172:175], v[198:201], v[54:57]
	v_mfma_f32_16x16x32_bf16 v[94:97], v[164:167], v[206:209], v[94:97]
	v_mfma_f32_16x16x32_bf16 v[86:89], v[172:175], v[206:209], v[86:89]
	s_setprio 0
	s_barrier
	s_add_i32 s67, 16, 0x14000
	v_lshl_add_u64 v[230:231], v[150:151], 0, s[54:55]
	s_add_i32 s61, s61, s62
	v_add_u32_e32 v196, s67, v159
	v_lshl_add_u64 v[232:233], v[230:231], 0, s[44:45]
	s_mov_b32 m0, s61
	ds_read_b128 v[210:213], v196
	ds_read_b128 v[214:217], v196 offset:1024
	ds_read_b128 v[218:221], v196 offset:2048
	ds_read_b128 v[222:225], v196 offset:3072
	global_load_lds_dwordx4 v[232:233], off
	v_lshl_add_u64 v[232:233], v[152:153], 0, s[54:55]
	v_lshl_add_u64 v[234:235], v[232:233], 0, s[44:45]
	s_add_i32 m0, s61, 0x2000
	s_nop 0
	global_load_lds_dwordx4 v[234:235], off
	s_barrier
	s_waitcnt lgkmcnt(0)
	s_setprio 1
	s_waitcnt lgkmcnt(0)
	v_mfma_f32_16x16x32_bf16 v[6:9], v[210:213], v[176:179], v[6:9]
	v_mfma_f32_16x16x32_bf16 v[2:5], v[218:221], v[176:179], v[2:5]
	v_mfma_f32_16x16x32_bf16 v[22:25], v[210:213], v[184:187], v[22:25]
	v_mfma_f32_16x16x32_bf16 v[18:21], v[218:221], v[184:187], v[18:21]
	v_mfma_f32_16x16x32_bf16 v[38:41], v[210:213], v[192:195], v[38:41]
	v_mfma_f32_16x16x32_bf16 v[34:37], v[218:221], v[192:195], v[34:37]
	v_mfma_f32_16x16x32_bf16 v[70:73], v[210:213], v[202:205], v[70:73]
	v_mfma_f32_16x16x32_bf16 v[66:69], v[218:221], v[202:205], v[66:69]
	v_mfma_f32_16x16x32_bf16 v[6:9], v[214:217], v[180:183], v[6:9]
	v_mfma_f32_16x16x32_bf16 v[2:5], v[222:225], v[180:183], v[2:5]
	v_mfma_f32_16x16x32_bf16 v[22:25], v[214:217], v[188:191], v[22:25]
	v_mfma_f32_16x16x32_bf16 v[18:21], v[222:225], v[188:191], v[18:21]
	v_mfma_f32_16x16x32_bf16 v[38:41], v[214:217], v[198:201], v[38:41]
	v_mfma_f32_16x16x32_bf16 v[34:37], v[222:225], v[198:201], v[34:37]
	v_mfma_f32_16x16x32_bf16 v[70:73], v[214:217], v[206:209], v[70:73]
	v_mfma_f32_16x16x32_bf16 v[66:69], v[222:225], v[206:209], v[66:69]
	s_setprio 0
	s_mov_b32 m0, s57
	v_lshl_add_u64 v[234:235], v[226:227], 0, s[44:45]
	s_barrier
	ds_read_b128 v[176:179], v158 offset:16384
	ds_read_b128 v[180:183], v158 offset:17408
	ds_read_b128 v[184:187], v158 offset:18432
	ds_read_b128 v[188:191], v158 offset:19456
	ds_read_b128 v[192:195], v158 offset:20480
	ds_read_b128 v[198:201], v158 offset:21504
	ds_read_b128 v[202:205], v158 offset:22528
	ds_read_b128 v[206:209], v158 offset:23552
	global_load_lds_dwordx4 v[234:235], off
	v_lshl_add_u64 v[234:235], v[228:229], 0, s[44:45]
	s_mov_b32 m0, s59
	s_nop 0
	global_load_lds_dwordx4 v[234:235], off
	s_barrier
	s_waitcnt lgkmcnt(0)
	s_setprio 1
	s_waitcnt lgkmcnt(0)
	v_mfma_f32_16x16x32_bf16 v[58:61], v[160:163], v[176:179], v[58:61]
	v_mfma_f32_16x16x32_bf16 v[50:53], v[168:171], v[176:179], v[50:53]
	v_mfma_f32_16x16x32_bf16 v[90:93], v[160:163], v[184:187], v[90:93]
	v_mfma_f32_16x16x32_bf16 v[82:85], v[168:171], v[184:187], v[82:85]
	v_mfma_f32_16x16x32_bf16 v[110:113], v[160:163], v[192:195], v[110:113]
	v_mfma_f32_16x16x32_bf16 v[106:109], v[168:171], v[192:195], v[106:109]
	v_mfma_f32_16x16x32_bf16 v[126:129], v[160:163], v[202:205], v[126:129]
	v_mfma_f32_16x16x32_bf16 v[122:125], v[168:171], v[202:205], v[122:125]
	v_mfma_f32_16x16x32_bf16 v[58:61], v[164:167], v[180:183], v[58:61]
	v_mfma_f32_16x16x32_bf16 v[50:53], v[172:175], v[180:183], v[50:53]
	v_mfma_f32_16x16x32_bf16 v[90:93], v[164:167], v[188:191], v[90:93]
	v_mfma_f32_16x16x32_bf16 v[82:85], v[172:175], v[188:191], v[82:85]
	v_mfma_f32_16x16x32_bf16 v[110:113], v[164:167], v[198:201], v[110:113]
	v_mfma_f32_16x16x32_bf16 v[106:109], v[172:175], v[198:201], v[106:109]
	v_mfma_f32_16x16x32_bf16 v[126:129], v[164:167], v[206:209], v[126:129]
	v_mfma_f32_16x16x32_bf16 v[122:125], v[172:175], v[206:209], v[122:125]
	s_setprio 0
	s_barrier
	s_add_i32 s61, s67, s62
	v_lshl_add_u64 v[160:161], v[230:231], 0, s[46:47]
	s_mov_b32 m0, s61
	s_nop 0
	global_load_lds_dwordx4 v[160:161], off
	v_lshl_add_u64 v[160:161], v[232:233], 0, s[46:47]
	s_add_i32 m0, s61, 0x2000
	s_nop 0
	global_load_lds_dwordx4 v[160:161], off
	s_waitcnt vmcnt(6)
	s_barrier
	s_setprio 1
	v_mfma_f32_16x16x32_bf16 v[46:49], v[210:213], v[176:179], v[46:49]
	v_mfma_f32_16x16x32_bf16 v[42:45], v[218:221], v[176:179], v[42:45]
	v_mfma_f32_16x16x32_bf16 v[78:81], v[210:213], v[184:187], v[78:81]
	v_mfma_f32_16x16x32_bf16 v[74:77], v[218:221], v[184:187], v[74:77]
	v_mfma_f32_16x16x32_bf16 v[102:105], v[210:213], v[192:195], v[102:105]
	v_mfma_f32_16x16x32_bf16 v[98:101], v[218:221], v[192:195], v[98:101]
	v_mfma_f32_16x16x32_bf16 v[118:121], v[210:213], v[202:205], v[118:121]
	v_mfma_f32_16x16x32_bf16 v[114:117], v[218:221], v[202:205], v[114:117]
	v_mfma_f32_16x16x32_bf16 v[46:49], v[214:217], v[180:183], v[46:49]
	v_mfma_f32_16x16x32_bf16 v[42:45], v[222:225], v[180:183], v[42:45]
	v_mfma_f32_16x16x32_bf16 v[78:81], v[214:217], v[188:191], v[78:81]
	v_mfma_f32_16x16x32_bf16 v[74:77], v[222:225], v[188:191], v[74:77]
	v_mfma_f32_16x16x32_bf16 v[102:105], v[214:217], v[198:201], v[102:105]
	v_mfma_f32_16x16x32_bf16 v[98:101], v[222:225], v[198:201], v[98:101]
	v_mfma_f32_16x16x32_bf16 v[118:121], v[214:217], v[206:209], v[118:121]
	v_mfma_f32_16x16x32_bf16 v[114:117], v[222:225], v[206:209], v[114:117]
	s_setprio 0
	s_add_i32 s61, 16, 0x18000
	v_add_u32_e32 v172, s61, v159
	s_barrier
	ds_read_b128 v[160:163], v172
	ds_read_b128 v[164:167], v172 offset:1024
	ds_read_b128 v[168:171], v172 offset:2048
	ds_read_b128 v[172:175], v172 offset:3072
	s_mov_b32 m0, s63
	v_lshl_add_u64 v[210:211], v[226:227], 0, s[46:47]
	ds_read_b128 v[176:179], v158 offset:32768
	ds_read_b128 v[180:183], v158 offset:33792
	ds_read_b128 v[184:187], v158 offset:34816
	ds_read_b128 v[188:191], v158 offset:35840
	ds_read_b128 v[192:195], v158 offset:36864
	ds_read_b128 v[198:201], v158 offset:37888
	ds_read_b128 v[202:205], v158 offset:38912
	ds_read_b128 v[206:209], v158 offset:39936
	global_load_lds_dwordx4 v[210:211], off
	v_lshl_add_u64 v[210:211], v[228:229], 0, s[46:47]
	s_mov_b32 m0, s64
	s_nop 0
	global_load_lds_dwordx4 v[210:211], off
	s_waitcnt lgkmcnt(8)
	s_barrier
	s_waitcnt lgkmcnt(0)
	s_setprio 1
	s_waitcnt lgkmcnt(0)
	v_mfma_f32_16x16x32_bf16 v[14:17], v[160:163], v[176:179], v[14:17]
	v_mfma_f32_16x16x32_bf16 v[10:13], v[168:171], v[176:179], v[10:13]
	v_mfma_f32_16x16x32_bf16 v[30:33], v[160:163], v[184:187], v[30:33]
	v_mfma_f32_16x16x32_bf16 v[26:29], v[168:171], v[184:187], v[26:29]
	v_mfma_f32_16x16x32_bf16 v[62:65], v[160:163], v[192:195], v[62:65]
	v_mfma_f32_16x16x32_bf16 v[54:57], v[168:171], v[192:195], v[54:57]
	v_mfma_f32_16x16x32_bf16 v[94:97], v[160:163], v[202:205], v[94:97]
	v_mfma_f32_16x16x32_bf16 v[86:89], v[168:171], v[202:205], v[86:89]
	v_mfma_f32_16x16x32_bf16 v[14:17], v[164:167], v[180:183], v[14:17]
	v_mfma_f32_16x16x32_bf16 v[10:13], v[172:175], v[180:183], v[10:13]
	v_mfma_f32_16x16x32_bf16 v[30:33], v[164:167], v[188:191], v[30:33]
	v_mfma_f32_16x16x32_bf16 v[26:29], v[172:175], v[188:191], v[26:29]
	v_mfma_f32_16x16x32_bf16 v[62:65], v[164:167], v[198:201], v[62:65]
	v_mfma_f32_16x16x32_bf16 v[54:57], v[172:175], v[198:201], v[54:57]
	v_mfma_f32_16x16x32_bf16 v[94:97], v[164:167], v[206:209], v[94:97]
	v_mfma_f32_16x16x32_bf16 v[86:89], v[172:175], v[206:209], v[86:89]
	s_setprio 0
	s_barrier
	s_add_i32 s67, 16, 0x1c000
	s_add_i32 s61, s61, s62
	v_add_u32_e32 v196, s67, v159
	v_lshl_add_u64 v[234:235], v[230:231], 0, s[48:49]
	s_mov_b32 m0, s61
	ds_read_b128 v[210:213], v196
	ds_read_b128 v[214:217], v196 offset:1024
	ds_read_b128 v[218:221], v196 offset:2048
	ds_read_b128 v[222:225], v196 offset:3072
	global_load_lds_dwordx4 v[234:235], off
	v_lshl_add_u64 v[234:235], v[232:233], 0, s[48:49]
	s_add_i32 m0, s61, 0x2000
	s_nop 0
	global_load_lds_dwordx4 v[234:235], off
	s_barrier
	s_waitcnt lgkmcnt(0)
	s_setprio 1
	s_waitcnt lgkmcnt(0)
	v_mfma_f32_16x16x32_bf16 v[6:9], v[210:213], v[176:179], v[6:9]
	v_mfma_f32_16x16x32_bf16 v[2:5], v[218:221], v[176:179], v[2:5]
	v_mfma_f32_16x16x32_bf16 v[22:25], v[210:213], v[184:187], v[22:25]
	v_mfma_f32_16x16x32_bf16 v[18:21], v[218:221], v[184:187], v[18:21]
	v_mfma_f32_16x16x32_bf16 v[38:41], v[210:213], v[192:195], v[38:41]
	v_mfma_f32_16x16x32_bf16 v[34:37], v[218:221], v[192:195], v[34:37]
	v_mfma_f32_16x16x32_bf16 v[70:73], v[210:213], v[202:205], v[70:73]
	v_mfma_f32_16x16x32_bf16 v[66:69], v[218:221], v[202:205], v[66:69]
	v_mfma_f32_16x16x32_bf16 v[6:9], v[214:217], v[180:183], v[6:9]
	v_mfma_f32_16x16x32_bf16 v[2:5], v[222:225], v[180:183], v[2:5]
	v_mfma_f32_16x16x32_bf16 v[22:25], v[214:217], v[188:191], v[22:25]
	v_mfma_f32_16x16x32_bf16 v[18:21], v[222:225], v[188:191], v[18:21]
	v_mfma_f32_16x16x32_bf16 v[38:41], v[214:217], v[198:201], v[38:41]
	v_mfma_f32_16x16x32_bf16 v[34:37], v[222:225], v[198:201], v[34:37]
	v_mfma_f32_16x16x32_bf16 v[70:73], v[214:217], v[206:209], v[70:73]
	v_mfma_f32_16x16x32_bf16 v[66:69], v[222:225], v[206:209], v[66:69]
	s_setprio 0
	s_mov_b32 m0, s65
	v_lshl_add_u64 v[226:227], v[226:227], 0, s[48:49]
	s_barrier
	ds_read_b128 v[176:179], v158 offset:49152
	ds_read_b128 v[180:183], v158 offset:50176
	ds_read_b128 v[184:187], v158 offset:51200
	ds_read_b128 v[188:191], v158 offset:52224
	ds_read_b128 v[192:195], v158 offset:53248
	ds_read_b128 v[198:201], v158 offset:54272
	ds_read_b128 v[202:205], v158 offset:55296
	ds_read_b128 v[206:209], v158 offset:56320
	global_load_lds_dwordx4 v[226:227], off
	v_lshl_add_u64 v[226:227], v[228:229], 0, s[48:49]
	s_mov_b32 m0, s66
	s_nop 0
	global_load_lds_dwordx4 v[226:227], off
	s_barrier
	s_waitcnt lgkmcnt(0)
	s_setprio 1
	s_waitcnt lgkmcnt(0)
	v_mfma_f32_16x16x32_bf16 v[58:61], v[160:163], v[176:179], v[58:61]
	v_mfma_f32_16x16x32_bf16 v[50:53], v[168:171], v[176:179], v[50:53]
	v_mfma_f32_16x16x32_bf16 v[90:93], v[160:163], v[184:187], v[90:93]
	v_mfma_f32_16x16x32_bf16 v[82:85], v[168:171], v[184:187], v[82:85]
	v_mfma_f32_16x16x32_bf16 v[110:113], v[160:163], v[192:195], v[110:113]
	v_mfma_f32_16x16x32_bf16 v[106:109], v[168:171], v[192:195], v[106:109]
	v_mfma_f32_16x16x32_bf16 v[126:129], v[160:163], v[202:205], v[126:129]
	v_mfma_f32_16x16x32_bf16 v[122:125], v[168:171], v[202:205], v[122:125]
	v_mfma_f32_16x16x32_bf16 v[58:61], v[164:167], v[180:183], v[58:61]
	v_mfma_f32_16x16x32_bf16 v[50:53], v[172:175], v[180:183], v[50:53]
	v_mfma_f32_16x16x32_bf16 v[90:93], v[164:167], v[188:191], v[90:93]
	v_mfma_f32_16x16x32_bf16 v[82:85], v[172:175], v[188:191], v[82:85]
	v_mfma_f32_16x16x32_bf16 v[110:113], v[164:167], v[198:201], v[110:113]
	v_mfma_f32_16x16x32_bf16 v[106:109], v[172:175], v[198:201], v[106:109]
	v_mfma_f32_16x16x32_bf16 v[126:129], v[164:167], v[206:209], v[126:129]
	v_mfma_f32_16x16x32_bf16 v[122:125], v[172:175], v[206:209], v[122:125]
	s_setprio 0
	s_barrier
	s_add_i32 s61, s67, s62
	v_lshl_add_u64 v[160:161], v[230:231], 0, s[50:51]
	s_mov_b32 m0, s61
	s_nop 0
	global_load_lds_dwordx4 v[160:161], off
	v_lshl_add_u64 v[160:161], v[232:233], 0, s[50:51]
	s_add_i32 m0, s61, 0x2000
	s_nop 0
	global_load_lds_dwordx4 v[160:161], off
	s_waitcnt vmcnt(6)
	s_barrier
	s_setprio 1
	v_mfma_f32_16x16x32_bf16 v[46:49], v[210:213], v[176:179], v[46:49]
	v_mfma_f32_16x16x32_bf16 v[42:45], v[218:221], v[176:179], v[42:45]
	v_mfma_f32_16x16x32_bf16 v[78:81], v[210:213], v[184:187], v[78:81]
	v_mfma_f32_16x16x32_bf16 v[74:77], v[218:221], v[184:187], v[74:77]
	v_mfma_f32_16x16x32_bf16 v[102:105], v[210:213], v[192:195], v[102:105]
	v_mfma_f32_16x16x32_bf16 v[98:101], v[218:221], v[192:195], v[98:101]
	v_mfma_f32_16x16x32_bf16 v[118:121], v[210:213], v[202:205], v[118:121]
	v_mfma_f32_16x16x32_bf16 v[114:117], v[218:221], v[202:205], v[114:117]
	v_mfma_f32_16x16x32_bf16 v[46:49], v[214:217], v[180:183], v[46:49]
	v_mfma_f32_16x16x32_bf16 v[42:45], v[222:225], v[180:183], v[42:45]
	v_mfma_f32_16x16x32_bf16 v[78:81], v[214:217], v[188:191], v[78:81]
	v_mfma_f32_16x16x32_bf16 v[74:77], v[222:225], v[188:191], v[74:77]
	v_mfma_f32_16x16x32_bf16 v[102:105], v[214:217], v[198:201], v[102:105]
	v_mfma_f32_16x16x32_bf16 v[98:101], v[222:225], v[198:201], v[98:101]
	v_mfma_f32_16x16x32_bf16 v[118:121], v[214:217], v[206:209], v[118:121]
	v_mfma_f32_16x16x32_bf16 v[114:117], v[222:225], v[206:209], v[114:117]
	s_setprio 0
	s_add_i32 s56, s56, 2
	s_add_u32 s54, s54, 0x100
	s_addc_u32 s55, s55, 0
	s_cmp_gt_u32 s56, 11
	s_barrier
	s_cbranch_scc0 .LBB0_528
	s_add_u32 s52, s52, 0x40780
	v_add_u32_e32 v159, 16, v159
	s_addc_u32 s53, s53, 0
	s_mov_b32 m0, s60
	v_add_u32_e32 v164, 0x10000, v159
	v_lshl_add_u64 v[202:203], s[52:53], 0, v[130:131]
	ds_read_b128 v[146:149], v164
	ds_read_b128 v[150:153], v164 offset:1024
	ds_read_b128 v[160:163], v164 offset:2048
	ds_read_b128 v[164:167], v164 offset:3072
	ds_read_b128 v[168:171], v158
	ds_read_b128 v[172:175], v158 offset:1024
	ds_read_b128 v[176:179], v158 offset:2048
	ds_read_b128 v[180:183], v158 offset:3072
	ds_read_b128 v[184:187], v158 offset:4096
	ds_read_b128 v[188:191], v158 offset:5120
	ds_read_b128 v[192:195], v158 offset:6144
	ds_read_b128 v[198:201], v158 offset:7168
	global_load_lds_dwordx4 v[202:203], off
	v_lshl_add_u64 v[202:203], s[52:53], 0, v[134:135]
	s_mov_b32 m0, s58
	s_nop 0
	global_load_lds_dwordx4 v[202:203], off
	s_barrier
	s_waitcnt lgkmcnt(0)
	s_setprio 1
	s_waitcnt lgkmcnt(0)
	v_mfma_f32_16x16x32_bf16 v[14:17], v[146:149], v[168:171], v[14:17]
	v_mfma_f32_16x16x32_bf16 v[10:13], v[160:163], v[168:171], v[10:13]
	v_mfma_f32_16x16x32_bf16 v[30:33], v[146:149], v[176:179], v[30:33]
	v_mfma_f32_16x16x32_bf16 v[26:29], v[160:163], v[176:179], v[26:29]
	v_mfma_f32_16x16x32_bf16 v[62:65], v[146:149], v[184:187], v[62:65]
	v_mfma_f32_16x16x32_bf16 v[54:57], v[160:163], v[184:187], v[54:57]
	v_mfma_f32_16x16x32_bf16 v[94:97], v[146:149], v[192:195], v[94:97]
	v_mfma_f32_16x16x32_bf16 v[86:89], v[160:163], v[192:195], v[86:89]
	v_mfma_f32_16x16x32_bf16 v[14:17], v[150:153], v[172:175], v[14:17]
	v_mfma_f32_16x16x32_bf16 v[10:13], v[164:167], v[172:175], v[10:13]
	v_mfma_f32_16x16x32_bf16 v[30:33], v[150:153], v[180:183], v[30:33]
	v_mfma_f32_16x16x32_bf16 v[26:29], v[164:167], v[180:183], v[26:29]
	v_mfma_f32_16x16x32_bf16 v[62:65], v[150:153], v[188:191], v[62:65]
	v_mfma_f32_16x16x32_bf16 v[54:57], v[164:167], v[188:191], v[54:57]
	v_mfma_f32_16x16x32_bf16 v[94:97], v[150:153], v[198:201], v[94:97]
	v_mfma_f32_16x16x32_bf16 v[86:89], v[164:167], v[198:201], v[86:89]
	s_setprio 0
	v_add_u32_e32 v196, 0x14000, v159
	s_barrier
	ds_read_b128 v[202:205], v196
	ds_read_b128 v[206:209], v196 offset:1024
	ds_read_b128 v[210:213], v196 offset:2048
	ds_read_b128 v[214:217], v196 offset:3072
	s_barrier
	s_waitcnt lgkmcnt(0)
	s_setprio 1
	s_waitcnt lgkmcnt(0)
	v_mfma_f32_16x16x32_bf16 v[2:5], v[210:213], v[168:171], v[2:5]
	v_mfma_f32_16x16x32_bf16 v[6:9], v[202:205], v[168:171], v[6:9]
	v_mfma_f32_16x16x32_bf16 v[168:171], v[214:217], v[172:175], v[2:5]
	v_mfma_f32_16x16x32_bf16 v[2:5], v[202:205], v[176:179], v[22:25]
	v_mfma_f32_16x16x32_bf16 v[218:221], v[206:209], v[172:175], v[6:9]
	v_mfma_f32_16x16x32_bf16 v[172:175], v[206:209], v[180:183], v[2:5]
	v_mfma_f32_16x16x32_bf16 v[2:5], v[210:213], v[176:179], v[18:21]
	v_mfma_f32_16x16x32_bf16 v[176:179], v[214:217], v[180:183], v[2:5]
	v_mfma_f32_16x16x32_bf16 v[2:5], v[202:205], v[184:187], v[38:41]
	v_mfma_f32_16x16x32_bf16 v[180:183], v[206:209], v[188:191], v[2:5]
	v_mfma_f32_16x16x32_bf16 v[2:5], v[210:213], v[184:187], v[34:37]
	v_mfma_f32_16x16x32_bf16 v[184:187], v[214:217], v[188:191], v[2:5]
	v_mfma_f32_16x16x32_bf16 v[2:5], v[202:205], v[192:195], v[70:73]
	v_mfma_f32_16x16x32_bf16 v[70:73], v[206:209], v[198:201], v[2:5]
	v_mfma_f32_16x16x32_bf16 v[2:5], v[210:213], v[192:195], v[66:69]
	v_mfma_f32_16x16x32_bf16 v[66:69], v[214:217], v[198:201], v[2:5]
	s_setprio 0
	s_barrier
	s_nop 4
	ds_read_b128 v[2:5], v158 offset:16384
	ds_read_b128 v[6:9], v158 offset:17408
	ds_read_b128 v[18:21], v158 offset:18432
	ds_read_b128 v[22:25], v158 offset:19456
	ds_read_b128 v[34:37], v158 offset:20480
	ds_read_b128 v[38:41], v158 offset:21504
	ds_read_b128 v[188:191], v158 offset:22528
	ds_read_b128 v[192:195], v158 offset:23552
	s_waitcnt vmcnt(4)
	s_barrier
	s_waitcnt lgkmcnt(0)
	s_setprio 1
	s_waitcnt lgkmcnt(0)
	v_mfma_f32_16x16x32_bf16 v[50:53], v[160:163], v[2:5], v[50:53]
	v_mfma_f32_16x16x32_bf16 v[222:225], v[164:167], v[6:9], v[50:53]
	v_mfma_f32_16x16x32_bf16 v[50:53], v[146:149], v[18:21], v[90:93]
	v_mfma_f32_16x16x32_bf16 v[90:93], v[150:153], v[22:25], v[50:53]
	v_mfma_f32_16x16x32_bf16 v[50:53], v[160:163], v[18:21], v[82:85]
	v_mfma_f32_16x16x32_bf16 v[226:229], v[164:167], v[22:25], v[50:53]
	v_mfma_f32_16x16x32_bf16 v[50:53], v[146:149], v[34:37], v[110:113]
	v_mfma_f32_16x16x32_bf16 v[110:113], v[150:153], v[38:41], v[50:53]
	v_mfma_f32_16x16x32_bf16 v[50:53], v[160:163], v[34:37], v[106:109]
	v_mfma_f32_16x16x32_bf16 v[106:109], v[164:167], v[38:41], v[50:53]
	v_mfma_f32_16x16x32_bf16 v[50:53], v[146:149], v[188:191], v[126:129]
	v_mfma_f32_16x16x32_bf16 v[126:129], v[150:153], v[192:195], v[50:53]
	v_mfma_f32_16x16x32_bf16 v[50:53], v[160:163], v[188:191], v[122:125]
	v_mfma_f32_16x16x32_bf16 v[58:61], v[146:149], v[2:5], v[58:61]
	v_mfma_f32_16x16x32_bf16 v[122:125], v[164:167], v[192:195], v[50:53]
	v_mfma_f32_16x16x32_bf16 v[198:201], v[150:153], v[6:9], v[58:61]
	s_setprio 0
	s_setprio 1
	v_mfma_f32_16x16x32_bf16 v[46:49], v[202:205], v[2:5], v[46:49]
	v_mfma_f32_16x16x32_bf16 v[2:5], v[210:213], v[2:5], v[42:45]
	v_mfma_f32_16x16x32_bf16 v[150:153], v[214:217], v[6:9], v[2:5]
	v_mfma_f32_16x16x32_bf16 v[2:5], v[202:205], v[18:21], v[78:81]
	v_mfma_f32_16x16x32_bf16 v[160:163], v[206:209], v[22:25], v[2:5]
	v_mfma_f32_16x16x32_bf16 v[2:5], v[210:213], v[18:21], v[74:77]
	v_mfma_f32_16x16x32_bf16 v[164:167], v[214:217], v[22:25], v[2:5]
	v_mfma_f32_16x16x32_bf16 v[2:5], v[202:205], v[34:37], v[102:105]
	v_mfma_f32_16x16x32_bf16 v[230:233], v[206:209], v[38:41], v[2:5]
	v_mfma_f32_16x16x32_bf16 v[2:5], v[210:213], v[34:37], v[98:101]
	v_mfma_f32_16x16x32_bf16 v[98:101], v[214:217], v[38:41], v[2:5]
	v_mfma_f32_16x16x32_bf16 v[2:5], v[202:205], v[188:191], v[118:121]
	v_mfma_f32_16x16x32_bf16 v[202:205], v[206:209], v[192:195], v[2:5]
	v_mfma_f32_16x16x32_bf16 v[2:5], v[210:213], v[188:191], v[114:117]
	v_mfma_f32_16x16x32_bf16 v[146:149], v[206:209], v[6:9], v[46:49]
	v_mfma_f32_16x16x32_bf16 v[188:191], v[214:217], v[192:195], v[2:5]
	s_setprio 0
	s_nop 4
	v_add_u32_e32 v2, 0x18000, v159
	s_barrier
	ds_read_b128 v[78:81], v2
	ds_read_b128 v[102:105], v2 offset:1024
	ds_read_b128 v[114:117], v2 offset:2048
	ds_read_b128 v[118:121], v2 offset:3072
	ds_read_b128 v[38:41], v158 offset:32768
	ds_read_b128 v[42:45], v158 offset:33792
	ds_read_b128 v[46:49], v158 offset:34816
	ds_read_b128 v[58:61], v158 offset:35840
	ds_read_b128 v[74:77], v158 offset:36864
	ds_read_b128 v[82:85], v158 offset:37888
	ds_read_b128 v[192:195], v158 offset:38912
	ds_read_b128 v[206:209], v158 offset:39936
	s_waitcnt vmcnt(2)
	s_barrier
	s_waitcnt lgkmcnt(0)
	s_setprio 1
	s_waitcnt lgkmcnt(0)
	v_mfma_f32_16x16x32_bf16 v[2:5], v[78:81], v[38:41], v[14:17]
	v_mfma_f32_16x16x32_bf16 v[6:9], v[114:117], v[38:41], v[10:13]
	v_mfma_f32_16x16x32_bf16 v[10:13], v[114:117], v[46:49], v[26:29]
	v_mfma_f32_16x16x32_bf16 v[14:17], v[114:117], v[74:77], v[54:57]
	v_mfma_f32_16x16x32_bf16 v[18:21], v[118:121], v[42:45], v[6:9]
	v_mfma_f32_16x16x32_bf16 v[6:9], v[78:81], v[46:49], v[30:33]
	v_mfma_f32_16x16x32_bf16 v[22:25], v[118:121], v[58:61], v[10:13]
	v_mfma_f32_16x16x32_bf16 v[10:13], v[78:81], v[74:77], v[62:65]
	v_mfma_f32_16x16x32_bf16 v[26:29], v[118:121], v[82:85], v[14:17]
	v_mfma_f32_16x16x32_bf16 v[14:17], v[78:81], v[192:195], v[94:97]
	v_mfma_f32_16x16x32_bf16 v[30:33], v[114:117], v[192:195], v[86:89]
	v_mfma_f32_16x16x32_bf16 v[2:5], v[102:105], v[42:45], v[2:5]
	v_mfma_f32_16x16x32_bf16 v[6:9], v[102:105], v[58:61], v[6:9]
	v_mfma_f32_16x16x32_bf16 v[10:13], v[102:105], v[82:85], v[10:13]
	v_mfma_f32_16x16x32_bf16 v[14:17], v[102:105], v[206:209], v[14:17]
	v_mfma_f32_16x16x32_bf16 v[30:33], v[118:121], v[206:209], v[30:33]
	s_setprio 0
	v_add_u32_e32 v34, 0x1c000, v159
	s_barrier
	ds_read_b128 v[210:213], v34
	ds_read_b128 v[214:217], v34 offset:1024
	ds_read_b128 v[234:237], v34 offset:2048
	ds_read_b128 v[238:241], v34 offset:3072
	s_waitcnt vmcnt(0)
	s_barrier
	s_waitcnt lgkmcnt(0)
	s_setprio 1
	s_waitcnt lgkmcnt(0)
	v_mfma_f32_16x16x32_bf16 v[34:37], v[210:213], v[38:41], v[218:221]
	v_mfma_f32_16x16x32_bf16 v[38:41], v[234:237], v[38:41], v[168:171]
	v_mfma_f32_16x16x32_bf16 v[34:37], v[214:217], v[42:45], v[34:37]
	v_mfma_f32_16x16x32_bf16 v[50:53], v[238:241], v[42:45], v[38:41]
	v_mfma_f32_16x16x32_bf16 v[38:41], v[210:213], v[46:49], v[172:175]
	v_mfma_f32_16x16x32_bf16 v[42:45], v[234:237], v[46:49], v[176:179]
	v_mfma_f32_16x16x32_bf16 v[46:49], v[234:237], v[74:77], v[184:187]
	v_mfma_f32_16x16x32_bf16 v[38:41], v[214:217], v[58:61], v[38:41]
	v_mfma_f32_16x16x32_bf16 v[54:57], v[238:241], v[58:61], v[42:45]
	v_mfma_f32_16x16x32_bf16 v[42:45], v[210:213], v[74:77], v[180:183]
	v_mfma_f32_16x16x32_bf16 v[58:61], v[238:241], v[82:85], v[46:49]
	v_mfma_f32_16x16x32_bf16 v[46:49], v[210:213], v[192:195], v[70:73]
	v_mfma_f32_16x16x32_bf16 v[62:65], v[234:237], v[192:195], v[66:69]
	v_mfma_f32_16x16x32_bf16 v[42:45], v[214:217], v[82:85], v[42:45]
	v_mfma_f32_16x16x32_bf16 v[46:49], v[214:217], v[206:209], v[46:49]
	v_mfma_f32_16x16x32_bf16 v[62:65], v[238:241], v[206:209], v[62:65]
	s_setprio 0
	s_barrier
	ds_read_b128 v[168:171], v158 offset:49152
	ds_read_b128 v[172:175], v158 offset:50176
	ds_read_b128 v[176:179], v158 offset:51200
	ds_read_b128 v[180:183], v158 offset:52224
	ds_read_b128 v[184:187], v158 offset:53248
	ds_read_b128 v[192:195], v158 offset:54272
	ds_read_b128 v[206:209], v158 offset:55296
	ds_read_b128 v[218:221], v158 offset:56320
	s_barrier
	s_waitcnt lgkmcnt(0)
	s_setprio 1
	s_waitcnt lgkmcnt(0)
	v_mfma_f32_16x16x32_bf16 v[70:73], v[114:117], v[168:171], v[222:225]
	v_mfma_f32_16x16x32_bf16 v[74:77], v[114:117], v[176:179], v[226:229]
	v_mfma_f32_16x16x32_bf16 v[66:69], v[78:81], v[168:171], v[198:201]
	v_mfma_f32_16x16x32_bf16 v[82:85], v[118:121], v[172:175], v[70:73]
	v_mfma_f32_16x16x32_bf16 v[70:73], v[78:81], v[176:179], v[90:93]
	v_mfma_f32_16x16x32_bf16 v[86:89], v[118:121], v[180:183], v[74:77]
	v_mfma_f32_16x16x32_bf16 v[74:77], v[78:81], v[184:187], v[110:113]
	v_mfma_f32_16x16x32_bf16 v[90:93], v[114:117], v[184:187], v[106:109]
	v_mfma_f32_16x16x32_bf16 v[78:81], v[78:81], v[206:209], v[126:129]
	v_mfma_f32_16x16x32_bf16 v[94:97], v[114:117], v[206:209], v[122:125]
	v_mfma_f32_16x16x32_bf16 v[66:69], v[102:105], v[172:175], v[66:69]
	v_mfma_f32_16x16x32_bf16 v[70:73], v[102:105], v[180:183], v[70:73]
	v_mfma_f32_16x16x32_bf16 v[74:77], v[102:105], v[192:195], v[74:77]
	v_mfma_f32_16x16x32_bf16 v[90:93], v[118:121], v[192:195], v[90:93]
	v_mfma_f32_16x16x32_bf16 v[78:81], v[102:105], v[218:221], v[78:81]
	v_mfma_f32_16x16x32_bf16 v[94:97], v[118:121], v[218:221], v[94:97]
	s_setprio 0
	s_setprio 1
	v_mfma_f32_16x16x32_bf16 v[98:101], v[234:237], v[184:187], v[98:101]
	v_mfma_f32_16x16x32_bf16 v[106:109], v[234:237], v[168:171], v[150:153]
	v_mfma_f32_16x16x32_bf16 v[110:113], v[234:237], v[176:179], v[164:167]
	v_mfma_f32_16x16x32_bf16 v[126:129], v[238:241], v[192:195], v[98:101]
	v_mfma_f32_16x16x32_bf16 v[98:101], v[210:213], v[206:209], v[202:205]
	v_mfma_f32_16x16x32_bf16 v[102:105], v[210:213], v[168:171], v[146:149]
	v_mfma_f32_16x16x32_bf16 v[118:121], v[238:241], v[172:175], v[106:109]
	v_mfma_f32_16x16x32_bf16 v[106:109], v[210:213], v[176:179], v[160:163]
	v_mfma_f32_16x16x32_bf16 v[122:125], v[238:241], v[180:183], v[110:113]
	v_mfma_f32_16x16x32_bf16 v[110:113], v[210:213], v[184:187], v[230:233]
	v_mfma_f32_16x16x32_bf16 v[114:117], v[214:217], v[218:221], v[98:101]
	v_mfma_f32_16x16x32_bf16 v[98:101], v[234:237], v[206:209], v[188:191]
	v_mfma_f32_16x16x32_bf16 v[102:105], v[214:217], v[172:175], v[102:105]
	v_mfma_f32_16x16x32_bf16 v[106:109], v[214:217], v[180:183], v[106:109]
	v_mfma_f32_16x16x32_bf16 v[110:113], v[214:217], v[192:195], v[110:113]
	v_mfma_f32_16x16x32_bf16 v[98:101], v[238:241], v[218:221], v[98:101]
	s_setprio 0
	s_add_i32 s100, s2, s33
	s_cmpk_ge_i32 s100, 0x100
	s_cbranch_scc1 .LBB0_524
	s_cmpk_lt_u32 s3, 0x100
	s_barrier
	s_cbranch_scc0 .LBB0_524
	s_barrier
	s_branch .LBB0_524
